# grid.sync replaced by flat monotonic-counter barrier (zeroed modctr block), s_sleep 1
# speedup vs baseline: 1.0272x; 1.0272x over previous
; __global__ void __launch_bounds__(NTH, 2) mega_kernel(Params p) {
;     ...
;   grid.sync();
.LBB0_188:
	v_lshrrev_b32_e32 v1, 20, v0
	v_lshrrev_b32_e32 v0, 10, v0
	v_or_b32_e32 v0, v0, v1
	s_movk_i32 s4, 0x3ff
	v_and_or_b32 v0, v0, s4, v220
	v_cmp_eq_u32_e64 s[72:73], 0, v0
	s_waitcnt vmcnt(0) lgkmcnt(0)
	s_barrier
	s_and_saveexec_b64 s[4:5], s[72:73]
	s_cbranch_execz .LBB0_198
	buffer_wbl2 sc1
	s_load_dwordx2 s[6:7], s[0:1], 0x158
	s_load_dword s8, s[0:1], 0x490
	v_mov_b32_e32 v0, 0
	v_mov_b32_e32 v1, 1
	s_waitcnt vmcnt(0) lgkmcnt(0)
	global_atomic_add v0, v1, s[6:7] offset:128
	s_mul_i32 s8, s8, 1
.Lgs1_poll:
	global_load_dword v2, v0, s[6:7] offset:128 sc1
	s_waitcnt vmcnt(0)
	v_cmp_gt_u32_e32 vcc, s8, v2
	s_cbranch_vccz .Lgs1_done
	s_sleep 1
	s_branch .Lgs1_poll
.Lgs1_done:
	buffer_inv sc1
	s_waitcnt vmcnt(0)

; #define RUNPH(k, call) for (int rep_ = 0; rep_ < (((REPMASK) >> (k)) & 1) + 1; ++rep_) { call; grid.sync(); }
; __global__ void __launch_bounds__(NTH, 2) mega_kernel(Params p) {
;     ...
;   RUNPH(2, phase2(p, smem))
.LBB0_302:
	s_waitcnt vmcnt(0) lgkmcnt(0)
	s_barrier
	s_and_saveexec_b64 s[4:5], s[72:73]
	s_cbranch_execz .LBB0_312
	buffer_wbl2 sc1
	s_load_dwordx2 s[6:7], s[0:1], 0x158
	s_load_dword s8, s[0:1], 0x490
	v_mov_b32_e32 v0, 0
	v_mov_b32_e32 v1, 1
	s_waitcnt vmcnt(0) lgkmcnt(0)
	global_atomic_add v0, v1, s[6:7] offset:128
	s_mul_i32 s8, s8, 2

; #define RUNPH(k, call) for (int rep_ = 0; rep_ < (((REPMASK) >> (k)) & 1) + 1; ++rep_) { call; grid.sync(); }
; __global__ void __launch_bounds__(NTH, 2) mega_kernel(Params p) {
;     ...
;   RUNPH(3, phase3(p, smem))
.LBB0_525:
	s_waitcnt vmcnt(0) lgkmcnt(0)
	s_barrier
	s_and_saveexec_b64 s[4:5], s[72:73]
	s_cbranch_execz .LBB0_535
	buffer_wbl2 sc1
	s_load_dwordx2 s[6:7], s[0:1], 0x158
	s_load_dword s8, s[0:1], 0x490
	v_mov_b32_e32 v0, 0
	v_mov_b32_e32 v1, 1
	s_waitcnt vmcnt(0) lgkmcnt(0)
	global_atomic_add v0, v1, s[6:7] offset:128
	s_mul_i32 s8, s8, 3

; #define RUNPH(k, call) for (int rep_ = 0; rep_ < (((REPMASK) >> (k)) & 1) + 1; ++rep_) { call; grid.sync(); }
; __global__ void __launch_bounds__(NTH, 2) mega_kernel(Params p) {
;     ...
;   RUNPH(4, phase4(p, smem))
.LBB0_645:
	s_waitcnt vmcnt(0) lgkmcnt(0)
	s_barrier
	s_and_saveexec_b64 s[4:5], s[72:73]
	s_cbranch_execz .LBB0_655
	buffer_wbl2 sc1
	s_load_dwordx2 s[6:7], s[0:1], 0x158
	s_load_dword s8, s[0:1], 0x490
	v_mov_b32_e32 v0, 0
	v_mov_b32_e32 v1, 1
	s_waitcnt vmcnt(0) lgkmcnt(0)
	global_atomic_add v0, v1, s[6:7] offset:128
	s_mul_i32 s8, s8, 4

; #define RUNPH(k, call) for (int rep_ = 0; rep_ < (((REPMASK) >> (k)) & 1) + 1; ++rep_) { call; grid.sync(); }
; __global__ void __launch_bounds__(NTH, 2) mega_kernel(Params p) {
;     ...
;   RUNPH(5, phase5(p, smem))
.LBB0_882:
	s_waitcnt vmcnt(0) lgkmcnt(0)
	s_barrier
	s_and_saveexec_b64 s[4:5], s[72:73]
	s_cbranch_execz .LBB0_892
	buffer_wbl2 sc1
	s_load_dwordx2 s[6:7], s[0:1], 0x158
	s_load_dword s8, s[0:1], 0x490
	v_mov_b32_e32 v0, 0
	v_mov_b32_e32 v1, 1
	s_waitcnt vmcnt(0) lgkmcnt(0)
	global_atomic_add v0, v1, s[6:7] offset:128
	s_mul_i32 s8, s8, 5

; #define RUNPH(k, call) for (int rep_ = 0; rep_ < (((REPMASK) >> (k)) & 1) + 1; ++rep_) { call; grid.sync(); }
; __global__ void __launch_bounds__(NTH, 2) mega_kernel(Params p) {
;     ...
;   RUNPH(6, phase6(p, smem))
.LBB0_929:
	s_waitcnt vmcnt(0) lgkmcnt(0)
	s_barrier
	s_and_saveexec_b64 s[4:5], s[72:73]
	s_cbranch_execz .LBB0_939
	buffer_wbl2 sc1
	s_load_dwordx2 s[6:7], s[0:1], 0x158
	s_load_dword s8, s[0:1], 0x490
	v_mov_b32_e32 v0, 0
	v_mov_b32_e32 v1, 1
	s_waitcnt vmcnt(0) lgkmcnt(0)
	global_atomic_add v0, v1, s[6:7] offset:128
	s_mul_i32 s8, s8, 6

; #define RUNPH(k, call) for (int rep_ = 0; rep_ < (((REPMASK) >> (k)) & 1) + 1; ++rep_) { call; grid.sync(); }
; __global__ void __launch_bounds__(NTH, 2) mega_kernel(Params p) {
;     ...
;   RUNPH(7, phase7(p, smem))
.LBB0_968:
	s_or_b64 exec, exec, s[18:19]
	s_waitcnt vmcnt(0) lgkmcnt(0)
	s_barrier
	s_and_saveexec_b64 s[4:5], s[72:73]
	s_cbranch_execz .LBB0_978
	buffer_wbl2 sc1
	s_load_dwordx2 s[6:7], s[0:1], 0x158
	s_load_dword s8, s[0:1], 0x490
	v_mov_b32_e32 v0, 0
	v_mov_b32_e32 v1, 1
	s_waitcnt vmcnt(0) lgkmcnt(0)
	global_atomic_add v0, v1, s[6:7] offset:128
	s_mul_i32 s8, s8, 7

; #define RUNPH(k, call) for (int rep_ = 0; rep_ < (((REPMASK) >> (k)) & 1) + 1; ++rep_) { call; grid.sync(); }
; __global__ void __launch_bounds__(NTH, 2) mega_kernel(Params p) {
;     ...
;   RUNPH(8, phase8(p))
.LBB0_1175:
	s_or_b64 exec, exec, s[88:89]
	s_waitcnt vmcnt(0) lgkmcnt(0)
	s_barrier
	s_and_saveexec_b64 s[4:5], s[72:73]
	s_cbranch_execz .LBB0_1185
	buffer_wbl2 sc1
	s_load_dwordx2 s[6:7], s[0:1], 0x158
	s_load_dword s8, s[0:1], 0x490
	v_mov_b32_e32 v0, 0
	v_mov_b32_e32 v1, 1
	s_waitcnt vmcnt(0) lgkmcnt(0)
	global_atomic_add v0, v1, s[6:7] offset:128
	s_mul_i32 s8, s8, 8

; __global__ void __launch_bounds__(NTH, 2) mega_kernel(Params p) {
;     ...
;   grid.sync();
.LBB0_1372:
	s_waitcnt vmcnt(0) lgkmcnt(0)
	s_barrier
	s_and_saveexec_b64 s[2:3], s[72:73]
	s_cbranch_execz .LBB0_1382
	buffer_wbl2 sc1
	s_load_dwordx2 s[6:7], s[0:1], 0x158
	s_load_dword s8, s[0:1], 0x490
	v_mov_b32_e32 v0, 0
	v_mov_b32_e32 v1, 1
	s_waitcnt vmcnt(0) lgkmcnt(0)
	global_atomic_add v0, v1, s[6:7] offset:128
	s_mul_i32 s8, s8, 9
